# P2b MoBA routing dot product written as per-element f32 mul/fma/add in the original order (drops 68 v_mov register shuffles per block that fed v_pk_fma pairs)
# speedup vs baseline: 1.0128x; 1.0006x over previous
; #define LAS __attribute__((address_space(3)))
; __device__ __forceinline__ void p2b_unit(int u, const bf16_t* H, const float* kmean, unsigned* ctl, unsigned* lists, LAS float* km, int tid) {
;     ...
;         for (int j = 0; j < own; ++j) { const LAS f32x4* kj = (const LAS f32x4*)(km + j * 64); float g0 = 0.f, g1 = 0.f;
; #pragma unroll
;             for (int i = 0; i < 16; i += 2) { const f32x4 ka = kj[i], kb = kj[i + 1]; g0 += q[4 * i] * ka[0] + q[4 * i + 1] * ka[1] + q[4 * i + 2] * ka[2] + q[4 * i + 3] * ka[3]; g1 += q[4 * i + 4] * kb[0] + q[4 * i + 5] * kb[1] + q[4 * i + 6] * kb[2] + q[4 * i + 7] * kb[3]; }
;             const float g = g0 + g1;
;             if (g > v0) { v2 = v1; i2 = i1; v1 = v0; i1 = i0; v0 = g; i0 = j; } else if (g > v1) { v2 = v1; i2 = i1; v1 = g; i1 = j; } else if (g > v2) { v2 = g; i2 = j; } }
.LBB0_276:
	v_mov_b32_e32 v140, s7
	ds_read_b128 v[80:83], v140
	ds_read_b128 v[84:87], v140 offset:16
	ds_read_b128 v[88:91], v140 offset:32
	ds_read_b128 v[92:95], v140 offset:48
	ds_read_b128 v[96:99], v140 offset:64
	ds_read_b128 v[100:103], v140 offset:80
	ds_read_b128 v[104:107], v140 offset:96
	ds_read_b128 v[108:111], v140 offset:112
	ds_read_b128 v[112:115], v140 offset:128
	ds_read_b128 v[116:119], v140 offset:144
	ds_read_b128 v[120:123], v140 offset:160
	ds_read_b128 v[124:127], v140 offset:176
	ds_read_b128 v[128:131], v140 offset:192
	ds_read_b128 v[132:135], v140 offset:208
	ds_read_b128 v[136:139], v140 offset:224
	ds_read_b128 v[140:143], v140 offset:240
	s_waitcnt lgkmcnt(14)
	v_mul_f32_e32 v144, v81, v62
	v_mul_f32_e32 v145, v85, v63
	v_fma_f32 v144, v80, v60, v144
	v_fma_f32 v145, v84, v61, v145
	v_fma_f32 v144, v82, v58, v144
	v_fma_f32 v145, v86, v59, v145
	v_fma_f32 v144, v83, v64, v144
	v_fma_f32 v145, v87, v65, v145
	v_add_f32_e32 v80, 0, v144
	v_add_f32_e32 v81, 0, v145
	s_waitcnt lgkmcnt(12)
	v_mul_f32_e32 v144, v89, v12
	v_mul_f32_e32 v145, v93, v13
	v_fma_f32 v144, v88, v10, v144
	v_fma_f32 v145, v92, v11, v145
	v_fma_f32 v144, v90, v14, v144
	v_fma_f32 v145, v94, v15, v145
	v_fma_f32 v144, v91, v16, v144
	v_fma_f32 v145, v95, v17, v145
	v_add_f32_e32 v80, v80, v144
	v_add_f32_e32 v81, v81, v145
	s_waitcnt lgkmcnt(10)
	v_mul_f32_e32 v144, v97, v20
	v_mul_f32_e32 v145, v101, v21
	v_fma_f32 v144, v96, v18, v144
	v_fma_f32 v145, v100, v19, v145
	v_fma_f32 v144, v98, v22, v144
	v_fma_f32 v145, v102, v23, v145
	v_fma_f32 v144, v99, v24, v144
	v_fma_f32 v145, v103, v25, v145
	v_add_f32_e32 v80, v80, v144
	v_add_f32_e32 v81, v81, v145
	s_waitcnt lgkmcnt(8)
	v_mul_f32_e32 v144, v105, v28
	v_mul_f32_e32 v145, v109, v29
	v_fma_f32 v144, v104, v26, v144
	v_fma_f32 v145, v108, v27, v145
	v_fma_f32 v144, v106, v30, v144
	v_fma_f32 v145, v110, v31, v145
	v_fma_f32 v144, v107, v32, v144
	v_fma_f32 v145, v111, v33, v145
	v_add_f32_e32 v80, v80, v144
	v_add_f32_e32 v81, v81, v145
	s_waitcnt lgkmcnt(6)
	v_mul_f32_e32 v144, v113, v36
	v_mul_f32_e32 v145, v117, v37
	v_fma_f32 v144, v112, v34, v144
	v_fma_f32 v145, v116, v35, v145
	v_fma_f32 v144, v114, v38, v144
	v_fma_f32 v145, v118, v39, v145
	v_fma_f32 v144, v115, v40, v144
	v_fma_f32 v145, v119, v41, v145
	v_add_f32_e32 v80, v80, v144
	v_add_f32_e32 v81, v81, v145
	s_waitcnt lgkmcnt(4)
	v_mul_f32_e32 v144, v121, v44
	v_mul_f32_e32 v145, v125, v45
	v_fma_f32 v144, v120, v42, v144
	v_fma_f32 v145, v124, v43, v145
	v_fma_f32 v144, v122, v46, v144
	v_fma_f32 v145, v126, v47, v145
	v_fma_f32 v144, v123, v48, v144
	v_fma_f32 v145, v127, v49, v145
	v_add_f32_e32 v80, v80, v144
	v_add_f32_e32 v81, v81, v145
	s_waitcnt lgkmcnt(2)
	v_mul_f32_e32 v144, v129, v52
	v_mul_f32_e32 v145, v133, v53
	v_fma_f32 v144, v128, v50, v144
	v_fma_f32 v145, v132, v51, v145
	v_fma_f32 v144, v130, v54, v144
	v_fma_f32 v145, v134, v55, v145
	v_fma_f32 v144, v131, v56, v144
	v_fma_f32 v145, v135, v57, v145
	v_add_f32_e32 v80, v80, v144
	v_add_f32_e32 v81, v81, v145
	s_waitcnt lgkmcnt(0)
	v_mul_f32_e32 v144, v137, v68
	v_mul_f32_e32 v145, v141, v69
	v_fma_f32 v144, v136, v66, v144
	v_fma_f32 v145, v140, v67, v145
	v_fma_f32 v144, v138, v70, v144
	v_fma_f32 v145, v142, v71, v145
	v_fma_f32 v144, v139, v72, v144
	v_fma_f32 v145, v143, v73, v145
	v_add_f32_e32 v80, v80, v144
	v_add_f32_e32 v81, v81, v145
	v_mov_b32_e32 v83, v0
	v_add_f32_e32 v82, v80, v81
	v_cmp_ngt_f32_e32 vcc, v82, v0
	v_mov_b32_e32 v81, s11
	v_mov_b32_e32 v80, v9
	s_and_saveexec_b64 s[28:29], vcc
	s_cbranch_execz .LBB0_282
	v_cmp_ngt_f32_e32 vcc, v82, v77
	v_mov_b32_e32 v80, s11
	s_and_saveexec_b64 s[36:37], vcc
	s_cbranch_execz .LBB0_281
	v_cmp_gt_f32_e32 vcc, v82, v79
	s_and_saveexec_b64 s[42:43], vcc
	v_mov_b32_e32 v3, s11
	v_mov_b32_e32 v79, v82
	s_or_b64 exec, exec, s[42:43]
	v_mov_b32_e32 v80, v78
	v_mov_b32_e32 v78, v3
	v_mov_b32_e32 v82, v77
	v_mov_b32_e32 v77, v79
